# MLA/SWA attention loops: the lgkmcnt(0) for the V fragments moved from the end of the QK segment (before the barrier) down to their first consumer, the PV MFMAs
# speedup vs baseline: 1.0616x; 1.0002x over previous
; DI unsigned pack2(float lo, float hi) { f32x2 v = {lo, hi}; bf16v2 r = __builtin_convertvector(v, bf16v2); return __builtin_bit_cast(unsigned, r); }
; DI float fexp2(float x) { return __builtin_amdgcn_exp2f(x); }
; template <int DQK, bool SWA, bool MASK, class KF, class VF>
; DI void attn_subtile(const bf16x8 (&qf)[DQK / 16], f32x16& o0, f32x16& o1, float& lsum, int kbase, int h, int qpos, int T, const LAS float* LUT, KF kfrag, VF vfrag) {
;     ...
;         float bias[16];
; #pragma unroll
;         for (int i = 0; i < 16; ++i) {
;             const int rel = kbase + (i & 3) + 8 * (i >> 2) + 4 * h - qpos;
;             const int idx = rel < -129 ? -129 : (rel > 129 ? 129 : rel); bias[i] = LUT[idx + 129];
;         }
; #pragma unroll
;         for (int i = 0; i < 16; ++i) {
;             const int kpos = kbase + (i & 3) + 8 * (i >> 2) + 4 * h, rel = kpos - qpos;
;             const float e = fexp2(s[i] + bias[i]);
;             const bool vis = kpos < T && (kpos < 16 || (rel <= 128 && rel >= -128));
;             pv[i] = vis ? e : 0.f; lsum += pv[i];
;         }
;     } else {
; #pragma unroll
;         for (int i = 0; i < 16; ++i) {
;             const float e = fexp2(s[i]);
;             if (MASK) { const int kpos = kbase + (i & 3) + 8 * (i >> 2) + 4 * h; pv[i] = kpos < T ? e : 0.f; } else pv[i] = e;
;             lsum += pv[i];
;         }
;     }
; #pragma unroll
;     for (int s2 = 0; s2 < 2; ++s2) {
;         u32x4 pk = {pack2(pv[8 * s2], pv[8 * s2 + 1]), pack2(pv[8 * s2 + 2], pv[8 * s2 + 3]), pack2(pv[8 * s2 + 4], pv[8 * s2 + 5]), pack2(pv[8 * s2 + 6], pv[8 * s2 + 7])};
;         const bf16x8 pf = __builtin_bit_cast(bf16x8, pk);
.Lswaa_xskip1:
	s_waitcnt vmcnt(6)
	s_barrier
	s_mov_b32 s28, s31
	s_add_u32 m0, s28, s24
	s_nop 0
	global_load_lds_dwordx4 v[186:187], off
	v_lshl_add_u64 v[186:187], v[186:187], 0, s[36:37]
	s_add_u32 m0, s28, s25
	s_nop 0
	global_load_lds_dwordx4 v[188:189], off
	v_lshl_add_u64 v[188:189], v[188:189], 0, s[38:39]
	s_add_u32 m0, s28, s26
	s_nop 0
	global_load_lds_dwordx4 v[190:191], off
	v_lshl_add_u64 v[190:191], v[190:191], 0, s[40:41]
	s_cmp_eq_u32 s42, 0
	s_cbranch_scc1 .Lswaa_y1
	s_cmp_eq_u32 s27, 0
	s_cbranch_scc1 .Lswaa_y0meta
	s_sub_u32 s5, s13, 1
	s_cmp_eq_u32 s27, s5
	s_cbranch_scc1 .Lswaa_y0last
	s_lshl_b32 s4, s27, 6
	v_add_u32_e32 v18, s4, v20
	v_lshlrev_b32_e32 v21, 2, v18
	ds_read_b32 v122, v21 offset:49920
	ds_read_b32 v123, v21 offset:49924
	ds_read_b32 v124, v21 offset:49928
	ds_read_b32 v125, v21 offset:49932
	ds_read_b32 v126, v21 offset:49952
	ds_read_b32 v127, v21 offset:49956
	ds_read_b32 v128, v21 offset:49960
	ds_read_b32 v129, v21 offset:49964
	ds_read_b32 v130, v21 offset:49984
	ds_read_b32 v131, v21 offset:49988
	ds_read_b32 v132, v21 offset:49992
	ds_read_b32 v133, v21 offset:49996
	ds_read_b32 v134, v21 offset:50016
	ds_read_b32 v135, v21 offset:50020
	ds_read_b32 v136, v21 offset:50024
	ds_read_b32 v137, v21 offset:50028
	s_waitcnt lgkmcnt(0)
	v_add_f32_e32 v58, v58, v122
	v_add_f32_e32 v59, v59, v123
	v_add_f32_e32 v60, v60, v124
	v_add_f32_e32 v61, v61, v125
	v_add_f32_e32 v62, v62, v126
	v_add_f32_e32 v63, v63, v127
	v_add_f32_e32 v64, v64, v128
	v_add_f32_e32 v65, v65, v129
	v_add_f32_e32 v66, v66, v130
	v_add_f32_e32 v67, v67, v131
	v_add_f32_e32 v68, v68, v132
	v_add_f32_e32 v69, v69, v133
	v_add_f32_e32 v70, v70, v134
	v_add_f32_e32 v71, v71, v135
	v_add_f32_e32 v72, v72, v136
	v_add_f32_e32 v73, v73, v137
	v_exp_f32_e32 v58, v58
	v_exp_f32_e32 v59, v59
	v_exp_f32_e32 v60, v60
	v_exp_f32_e32 v61, v61
	v_exp_f32_e32 v62, v62
	v_exp_f32_e32 v63, v63
	v_exp_f32_e32 v64, v64
	v_exp_f32_e32 v65, v65
	v_exp_f32_e32 v66, v66
	v_exp_f32_e32 v67, v67
	v_exp_f32_e32 v68, v68
	v_exp_f32_e32 v69, v69
	v_exp_f32_e32 v70, v70
	v_exp_f32_e32 v71, v71
	v_exp_f32_e32 v72, v72
	v_exp_f32_e32 v73, v73
	v_cvt_pk_bf16_f32 v170, v58, v59
	v_cvt_pk_bf16_f32 v171, v60, v61
	v_cvt_pk_bf16_f32 v172, v62, v63
	v_cvt_pk_bf16_f32 v173, v64, v65
	v_cvt_pk_bf16_f32 v174, v66, v67
	v_cvt_pk_bf16_f32 v175, v68, v69
	v_cvt_pk_bf16_f32 v176, v70, v71
	v_cvt_pk_bf16_f32 v177, v72, v73
	v_add_f32_e32 v192, v192, v58
	v_add_f32_e32 v193, v193, v59
	v_add_f32_e32 v192, v192, v60
	v_add_f32_e32 v193, v193, v61
	v_add_f32_e32 v192, v192, v62
	v_add_f32_e32 v193, v193, v63
	v_add_f32_e32 v192, v192, v64
	v_add_f32_e32 v193, v193, v65
	v_add_f32_e32 v192, v192, v66
	v_add_f32_e32 v193, v193, v67
	v_add_f32_e32 v192, v192, v68
	v_add_f32_e32 v193, v193, v69
	v_add_f32_e32 v192, v192, v70
	v_add_f32_e32 v193, v193, v71
	v_add_f32_e32 v192, v192, v72
	v_add_f32_e32 v193, v193, v73
	s_branch .Lswaa_y1

; #define LAS __attribute__((address_space(3)))
; DI float fexp2(float x) { return __builtin_amdgcn_exp2f(x); }
; template <int DQK, bool MASK>
; DI void attn_tile64(const bf16x8 (&qf)[DQK / 16], f32x16& o0, f32x16& o1, float& lsum, int kbase0, int r, int h, int T, const LAS unsigned char* Ksm, const LAS unsigned char* Vsm) {
;     constexpr int KP = DQK * 2 + 16, NKS = DQK / 16;
;     bf16x8 ka[2][NKS];
; #pragma unroll
;     for (int kt = 0; kt < 2; ++kt)
; #pragma unroll
;         for (int ks = 0; ks < NKS; ++ks) ka[kt][ks] = *(const LAS bf16x8*)(Ksm + (32 * kt + r) * KP + (16 * ks + 8 * h) * 2);
;     f32x16 sa[2];
; #pragma unroll
;     for (int kt = 0; kt < 2; ++kt)
; #pragma unroll
;         for (int i = 0; i < 16; ++i) sa[kt][i] = 0.f;
; #pragma unroll
;     for (int ks = 0; ks < NKS; ++ks)
; #pragma unroll
;         for (int kt = 0; kt < 2; ++kt) sa[kt] = MFMA32(ka[kt][ks], qf[ks], sa[kt]);
;     bf16x8 pf[2][2];
;     f32x2 ls2 = {0.f, 0.f};
; #pragma unroll
;     for (int kt = 0; kt < 2; ++kt) {
;         float pv[16];
; #pragma unroll
;         for (int i = 0; i < 16; ++i) {
;             const float sv = sa[kt][i];
;             if (MASK) { const int kpos = kbase0 + 32 * kt + (i & 3) + 8 * (i >> 2) + 4 * h; const float e = fexp2(sv); pv[i] = kpos < T ? e : 0.f; } else pv[i] = fexp2(sv);
;         }
; #pragma unroll
;         for (int i = 0; i < 16; i += 2) ls2 = ls2 + (f32x2){pv[i], pv[i + 1]};
; #pragma unroll
;         for (int s2 = 0; s2 < 2; ++s2) {
;             u32x4 pk = {pack2(pv[8 * s2], pv[8 * s2 + 1]), pack2(pv[8 * s2 + 2], pv[8 * s2 + 3]), pack2(pv[8 * s2 + 4], pv[8 * s2 + 5]), pack2(pv[8 * s2 + 6], pv[8 * s2 + 7])};
;             pf[kt][s2] = __builtin_bit_cast(bf16x8, pk);
;         }
;     }
;     lsum += ls2[0] + ls2[1];
;     bf16x8 vf[2][2][2];
; #pragma unroll
;     for (int kt = 0; kt < 2; ++kt)
; #pragma unroll
;         for (int s2 = 0; s2 < 2; ++s2)
; #pragma unroll
;             for (int dt = 0; dt < 2; ++dt) {
;                 const u32x2 a0 = *(const LAS u32x2*)(Vsm + (32 * dt + r) * 144 + (32 * kt + 16 * s2 + 4 * h) * 2), a1 = *(const LAS u32x2*)(Vsm + (32 * dt + r) * 144 + (32 * kt + 16 * s2 + 8 + 4 * h) * 2);
;                 u32x4 av = {a0[0], a0[1], a1[0], a1[1]}; vf[kt][s2][dt] = __builtin_bit_cast(bf16x8, av);
;             }
; #pragma unroll
;     for (int kt = 0; kt < 2; ++kt)
; #pragma unroll
.Lmlaa_noskew:
.Lmlaa_loop:
	v_add_u32_e32 v197, s30, v194
	v_add_u32_e32 v198, s30, v195
	v_add_u32_e32 v199, s30, v196
	ds_read_b128 v[90:93], v197 offset:0
	ds_read_b128 v[94:97], v197 offset:6656
	ds_read_b128 v[98:101], v197 offset:32
	ds_read_b128 v[102:105], v197 offset:6688
	ds_read_b128 v[106:109], v197 offset:64
	ds_read_b128 v[110:113], v197 offset:6720
	ds_read_b128 v[114:117], v197 offset:96
	ds_read_b128 v[118:121], v197 offset:6752
	ds_read_b128 v[122:125], v197 offset:128
	ds_read_b128 v[126:129], v197 offset:6784
	ds_read_b128 v[130:133], v197 offset:160
	ds_read_b128 v[134:137], v197 offset:6816
	s_waitcnt lgkmcnt(11)
	v_mfma_f32_32x32x16_bf16 v[58:73], v[90:93], v[2:5], 0
	ds_read_b64 v[138:139], v198 offset:0
	ds_read_b64 v[140:141], v198 offset:16
	s_waitcnt lgkmcnt(12)
	v_mfma_f32_32x32x16_bf16 v[74:89], v[94:97], v[2:5], 0
	ds_read_b64 v[142:143], v199 offset:0
	ds_read_b64 v[144:145], v199 offset:16
	s_waitcnt lgkmcnt(13)
	v_mfma_f32_32x32x16_bf16 v[58:73], v[98:101], v[6:9], v[58:73]
	ds_read_b64 v[146:147], v198 offset:32
	ds_read_b64 v[148:149], v198 offset:48
	s_waitcnt lgkmcnt(14)
	v_mfma_f32_32x32x16_bf16 v[74:89], v[102:105], v[6:9], v[74:89]
	ds_read_b64 v[150:151], v199 offset:32
	ds_read_b64 v[152:153], v199 offset:48
	s_waitcnt lgkmcnt(15)
	v_mfma_f32_32x32x16_bf16 v[58:73], v[106:109], v[10:13], v[58:73]
	ds_read_b64 v[154:155], v198 offset:64
	ds_read_b64 v[156:157], v198 offset:80
	s_waitcnt lgkmcnt(15)
	v_mfma_f32_32x32x16_bf16 v[74:89], v[110:113], v[10:13], v[74:89]
	ds_read_b64 v[158:159], v199 offset:64
	ds_read_b64 v[160:161], v199 offset:80
	s_waitcnt lgkmcnt(15)
	v_mfma_f32_32x32x16_bf16 v[58:73], v[114:117], v[14:17], v[58:73]
	ds_read_b64 v[162:163], v198 offset:96
	ds_read_b64 v[164:165], v198 offset:112
	s_waitcnt lgkmcnt(15)
	v_mfma_f32_32x32x16_bf16 v[74:89], v[118:121], v[14:17], v[74:89]
	ds_read_b64 v[166:167], v199 offset:96
	ds_read_b64 v[168:169], v199 offset:112
	s_waitcnt lgkmcnt(15)
	v_mfma_f32_32x32x16_bf16 v[58:73], v[122:125], v[18:21], v[58:73]
	s_waitcnt lgkmcnt(15)
	v_mfma_f32_32x32x16_bf16 v[74:89], v[126:129], v[18:21], v[74:89]
	s_waitcnt lgkmcnt(15)
	v_mfma_f32_32x32x16_bf16 v[58:73], v[130:133], v[22:25], v[58:73]
	s_waitcnt lgkmcnt(15)
	v_mfma_f32_32x32x16_bf16 v[74:89], v[134:137], v[22:25], v[74:89]
	s_waitcnt vmcnt(6)
	s_barrier
	s_add_u32 m0, s31, s24
	s_nop 0
	global_load_lds_dwordx4 v[186:187], off
	v_lshl_add_u64 v[186:187], v[186:187], 0, s[36:37]
	s_add_u32 m0, s31, s25
	s_nop 0
	global_load_lds_dwordx4 v[188:189], off
	v_lshl_add_u64 v[188:189], v[188:189], 0, s[38:39]
	s_add_u32 m0, s31, s26
	s_nop 0
	global_load_lds_dwordx4 v[190:191], off
	v_lshl_add_u64 v[190:191], v[190:191], 0, s[40:41]
	s_cmp_eq_u32 s14, s29
	s_cbranch_scc1 .Lmlaa_ylast
	s_nop 15
	v_exp_f32_e32 v58, v58
	v_exp_f32_e32 v59, v59
	v_exp_f32_e32 v60, v60
	v_exp_f32_e32 v61, v61
	v_exp_f32_e32 v62, v62
	v_exp_f32_e32 v63, v63
	v_exp_f32_e32 v64, v64
	v_exp_f32_e32 v65, v65
	v_exp_f32_e32 v66, v66
	v_exp_f32_e32 v67, v67
	v_exp_f32_e32 v68, v68
	v_exp_f32_e32 v69, v69
	v_exp_f32_e32 v70, v70
	v_exp_f32_e32 v71, v71
	v_exp_f32_e32 v72, v72
	v_exp_f32_e32 v73, v73
	v_cvt_pk_bf16_f32 v170, v58, v59
	v_cvt_pk_bf16_f32 v171, v60, v61
	v_cvt_pk_bf16_f32 v172, v62, v63
	v_cvt_pk_bf16_f32 v173, v64, v65
	v_cvt_pk_bf16_f32 v174, v66, v67
	v_cvt_pk_bf16_f32 v175, v68, v69
	v_cvt_pk_bf16_f32 v176, v70, v71
	v_cvt_pk_bf16_f32 v177, v72, v73
	v_exp_f32_e32 v74, v74
	v_exp_f32_e32 v75, v75
	v_exp_f32_e32 v76, v76
	v_exp_f32_e32 v77, v77
	v_exp_f32_e32 v78, v78
	v_exp_f32_e32 v79, v79
	v_exp_f32_e32 v80, v80
	v_exp_f32_e32 v81, v81
	v_exp_f32_e32 v82, v82
	v_exp_f32_e32 v83, v83
	v_exp_f32_e32 v84, v84
	v_exp_f32_e32 v85, v85
	v_exp_f32_e32 v86, v86
	v_exp_f32_e32 v87, v87
	v_exp_f32_e32 v88, v88
	v_exp_f32_e32 v89, v89
	v_cvt_pk_bf16_f32 v178, v74, v75
	v_cvt_pk_bf16_f32 v179, v76, v77
	v_cvt_pk_bf16_f32 v180, v78, v79
	v_cvt_pk_bf16_f32 v181, v80, v81
	v_cvt_pk_bf16_f32 v182, v82, v83
	v_cvt_pk_bf16_f32 v183, v84, v85
	v_cvt_pk_bf16_f32 v184, v86, v87
	v_cvt_pk_bf16_f32 v185, v88, v89
	v_add_f32_e32 v192, v192, v58
	v_add_f32_e32 v193, v193, v59
	v_add_f32_e32 v192, v192, v60
	v_add_f32_e32 v193, v193, v61
	v_add_f32_e32 v192, v192, v62
	v_add_f32_e32 v193, v193, v63
	v_add_f32_e32 v192, v192, v64
	v_add_f32_e32 v193, v193, v65
	v_add_f32_e32 v192, v192, v66
	v_add_f32_e32 v193, v193, v67
	v_add_f32_e32 v192, v192, v68
	v_add_f32_e32 v193, v193, v69
	v_add_f32_e32 v192, v192, v70
	v_add_f32_e32 v193, v193, v71
	v_add_f32_e32 v192, v192, v72
	v_add_f32_e32 v193, v193, v73
	v_add_f32_e32 v192, v192, v74
	v_add_f32_e32 v193, v193, v75
	v_add_f32_e32 v192, v192, v76
	v_add_f32_e32 v193, v193, v77
	v_add_f32_e32 v192, v192, v78
	v_add_f32_e32 v193, v193, v79
	v_add_f32_e32 v192, v192, v80
	v_add_f32_e32 v193, v193, v81
	v_add_f32_e32 v192, v192, v82
	v_add_f32_e32 v193, v193, v83
	v_add_f32_e32 v192, v192, v84
	v_add_f32_e32 v193, v193, v85
	v_add_f32_e32 v192, v192, v86
	v_add_f32_e32 v193, v193, v87
	v_add_f32_e32 v192, v192, v88
	v_add_f32_e32 v193, v193, v89
	s_waitcnt lgkmcnt(0)
	v_mfma_f32_32x32x16_bf16 v[26:41], v[138:141], v[170:173], v[26:41]
	v_mfma_f32_32x32x16_bf16 v[42:57], v[142:145], v[170:173], v[42:57]
	v_mfma_f32_32x32x16_bf16 v[26:41], v[146:149], v[174:177], v[26:41]
	v_mfma_f32_32x32x16_bf16 v[42:57], v[150:153], v[174:177], v[42:57]
	v_mfma_f32_32x32x16_bf16 v[26:41], v[154:157], v[178:181], v[26:41]
	v_mfma_f32_32x32x16_bf16 v[42:57], v[158:161], v[178:181], v[42:57]
	v_mfma_f32_32x32x16_bf16 v[26:41], v[162:165], v[182:185], v[26:41]
	v_mfma_f32_32x32x16_bf16 v[42:57], v[166:169], v[182:185], v[42:57]
	s_branch .Lmlaa_yend
; #define LAS __attribute__((address_space(3)))
; DI unsigned pack2(float lo, float hi) { f32x2 v = {lo, hi}; bf16v2 r = __builtin_convertvector(v, bf16v2); return __builtin_bit_cast(unsigned, r); }
; DI float fexp2(float x) { return __builtin_amdgcn_exp2f(x); }
; #define MFMA32(a, b, c) __builtin_amdgcn_mfma_f32_32x32x16_bf16((a), (b), (c), 0, 0, 0)
; template <int DQK, bool MASK>
; DI void attn_tile64(const bf16x8 (&qf)[DQK / 16], f32x16& o0, f32x16& o1, float& lsum, int kbase0, int r, int h, int T, const LAS unsigned char* Ksm, const LAS unsigned char* Vsm) {
;     ...
;         float pv[16];
; #pragma unroll
;         for (int i = 0; i < 16; ++i) {
;             const float sv = sa[kt][i];
;             if (MASK) { const int kpos = kbase0 + 32 * kt + (i & 3) + 8 * (i >> 2) + 4 * h; const float e = fexp2(sv); pv[i] = kpos < T ? e : 0.f; } else pv[i] = fexp2(sv);
;         }
; #pragma unroll
;         for (int i = 0; i < 16; i += 2) ls2 = ls2 + (f32x2){pv[i], pv[i + 1]};
; #pragma unroll
;         for (int s2 = 0; s2 < 2; ++s2) {
;             u32x4 pk = {pack2(pv[8 * s2], pv[8 * s2 + 1]), pack2(pv[8 * s2 + 2], pv[8 * s2 + 3]), pack2(pv[8 * s2 + 4], pv[8 * s2 + 5]), pack2(pv[8 * s2 + 6], pv[8 * s2 + 7])};
;             pf[kt][s2] = __builtin_bit_cast(bf16x8, pk);
;         }
;     }
;     lsum += ls2[0] + ls2[1];
;     bf16x8 vf[2][2][2];
; #pragma unroll
;     for (int kt = 0; kt < 2; ++kt)
; #pragma unroll
;         for (int s2 = 0; s2 < 2; ++s2)
; #pragma unroll
;             for (int dt = 0; dt < 2; ++dt) {
;                 const u32x2 a0 = *(const LAS u32x2*)(Vsm + (32 * dt + r) * 144 + (32 * kt + 16 * s2 + 4 * h) * 2), a1 = *(const LAS u32x2*)(Vsm + (32 * dt + r) * 144 + (32 * kt + 16 * s2 + 8 + 4 * h) * 2);
;                 u32x4 av = {a0[0], a0[1], a1[0], a1[1]}; vf[kt][s2][dt] = __builtin_bit_cast(bf16x8, av);
;             }
; #pragma unroll
;     for (int kt = 0; kt < 2; ++kt)
; #pragma unroll
;         for (int s2 = 0; s2 < 2; ++s2) { o0 = MFMA32(vf[kt][s2][0], pf[kt][s2], o0); o1 = MFMA32(vf[kt][s2][1], pf[kt][s2], o1); }
.Lmlaa_ylast:
	s_nop 15
	v_exp_f32_e32 v58, v58
	v_exp_f32_e32 v59, v59
	v_exp_f32_e32 v60, v60
	v_exp_f32_e32 v61, v61
	v_exp_f32_e32 v62, v62
	v_exp_f32_e32 v63, v63
	v_exp_f32_e32 v64, v64
	v_exp_f32_e32 v65, v65
	v_mov_b32_e32 v66, 0
	v_mov_b32_e32 v67, 0
	v_mov_b32_e32 v68, 0
	v_mov_b32_e32 v69, 0
	v_mov_b32_e32 v70, 0
	v_mov_b32_e32 v71, 0
	v_mov_b32_e32 v72, 0
	v_mov_b32_e32 v73, 0
	v_cvt_pk_bf16_f32 v170, v58, v59
	v_cvt_pk_bf16_f32 v171, v60, v61
	v_cvt_pk_bf16_f32 v172, v62, v63
	v_cvt_pk_bf16_f32 v173, v64, v65
	v_cvt_pk_bf16_f32 v174, v66, v67
	v_cvt_pk_bf16_f32 v175, v68, v69
	v_cvt_pk_bf16_f32 v176, v70, v71
	v_cvt_pk_bf16_f32 v177, v72, v73
	v_mov_b32_e32 v74, 0
	v_mov_b32_e32 v75, 0
	v_mov_b32_e32 v76, 0
	v_mov_b32_e32 v77, 0
	v_mov_b32_e32 v78, 0
	v_mov_b32_e32 v79, 0
	v_mov_b32_e32 v80, 0
	v_mov_b32_e32 v81, 0
	v_mov_b32_e32 v82, 0
	v_mov_b32_e32 v83, 0
	v_mov_b32_e32 v84, 0
	v_mov_b32_e32 v85, 0
	v_mov_b32_e32 v86, 0
	v_mov_b32_e32 v87, 0
	v_mov_b32_e32 v88, 0
	v_mov_b32_e32 v89, 0
	s_nop 0
	v_cvt_pk_bf16_f32 v178, v74, v75
	v_cvt_pk_bf16_f32 v179, v76, v77
	v_cvt_pk_bf16_f32 v180, v78, v79
	v_cvt_pk_bf16_f32 v181, v80, v81
	v_cvt_pk_bf16_f32 v182, v82, v83
	v_cvt_pk_bf16_f32 v183, v84, v85
	v_cvt_pk_bf16_f32 v184, v86, v87
	v_cvt_pk_bf16_f32 v185, v88, v89
	v_add_f32_e32 v192, v192, v58
	v_add_f32_e32 v193, v193, v59
	v_add_f32_e32 v192, v192, v60
	v_add_f32_e32 v193, v193, v61
	v_add_f32_e32 v192, v192, v62
	v_add_f32_e32 v193, v193, v63
	v_add_f32_e32 v192, v192, v64
	v_add_f32_e32 v193, v193, v65
	v_add_f32_e32 v192, v192, v66
	v_add_f32_e32 v193, v193, v67
	v_add_f32_e32 v192, v192, v68
	v_add_f32_e32 v193, v193, v69
	v_add_f32_e32 v192, v192, v70
	v_add_f32_e32 v193, v193, v71
	v_add_f32_e32 v192, v192, v72
	v_add_f32_e32 v193, v193, v73
	v_add_f32_e32 v192, v192, v74
	v_add_f32_e32 v193, v193, v75
	v_add_f32_e32 v192, v192, v76
	v_add_f32_e32 v193, v193, v77
	v_add_f32_e32 v192, v192, v78
	v_add_f32_e32 v193, v193, v79
	v_add_f32_e32 v192, v192, v80
	v_add_f32_e32 v193, v193, v81
	v_add_f32_e32 v192, v192, v82
	v_add_f32_e32 v193, v193, v83
	v_add_f32_e32 v192, v192, v84
	v_add_f32_e32 v193, v193, v85
	v_add_f32_e32 v192, v192, v86
	v_add_f32_e32 v193, v193, v87
	v_add_f32_e32 v192, v192, v88
	v_add_f32_e32 v193, v193, v89
	s_waitcnt lgkmcnt(0)
	v_mfma_f32_32x32x16_bf16 v[26:41], v[138:141], v[170:173], v[26:41]
	v_mfma_f32_32x32x16_bf16 v[42:57], v[142:145], v[170:173], v[42:57]
	v_mfma_f32_32x32x16_bf16 v[26:41], v[146:149], v[174:177], v[26:41]
	v_mfma_f32_32x32x16_bf16 v[42:57], v[150:153], v[174:177], v[42:57]
	v_mfma_f32_32x32x16_bf16 v[26:41], v[154:157], v[178:181], v[26:41]
	v_mfma_f32_32x32x16_bf16 v[42:57], v[158:161], v[178:181], v[42:57]
	v_mfma_f32_32x32x16_bf16 v[26:41], v[162:165], v[182:185], v[26:41]
	v_mfma_f32_32x32x16_bf16 v[42:57], v[166:169], v[182:185], v[42:57]
